# grid barrier: global-last leader bumps all XGEN words with one 16-lane atomic (no per-XCD relay)
# baseline (speedup 1.0000x reference)
.LBB0_727:
	s_or_b64 exec, exec, s[30:31]
	s_waitcnt vmcnt(0)
	v_readfirstlane_b32 s2, v3
	v_sub_u32_e32 v4, 0, v2
	v_readlane_b32 s12, v255, 10
	v_add_u32_e32 v3, s2, v0
	v_cvt_f32_u32_e32 v0, v2
	v_readlane_b32 s13, v255, 11
	s_mov_b64 s[30:31], -1
	v_rcp_iflag_f32_e32 v0, v0
	s_nop 0
	v_mul_f32_e32 v0, 0x4f7ffffe, v0
	v_cvt_u32_f32_e32 v0, v0
	v_mul_lo_u32 v4, v4, v0
	v_mul_hi_u32 v4, v0, v4
	v_add_u32_e32 v0, v0, v4
	v_mul_hi_u32 v0, v3, v0
	v_mul_lo_u32 v4, v0, v2
	v_sub_u32_e32 v4, v3, v4
	v_cmp_ge_u32_e32 vcc, v4, v2
	v_add_u32_e32 v5, 1, v0
	v_add_u32_e32 v3, 1, v3
	v_cndmask_b32_e32 v0, v0, v5, vcc
	v_sub_u32_e32 v5, v4, v2
	v_cndmask_b32_e32 v4, v4, v5, vcc
	v_cmp_ge_u32_e32 vcc, v4, v2
	v_add_u32_e32 v4, 1, v0
	s_nop 0
	v_cndmask_b32_e32 v0, v0, v4, vcc
	v_mul_lo_u32 v4, v2, v0
	v_add_u32_e32 v2, v4, v2
	v_cmp_ne_u32_e32 vcc, v3, v2
	v_mov_b64_e32 v[2:3], s[12:13]
	s_cbranch_vccnz .Lxb_notlast
	s_mov_b64 s[36:37], exec
	s_mov_b64 exec, 0xffff
	v_lshlrev_b32_e32 v4, 8, v231
	v_add_u32_e32 v4, 0x2000, v4
	global_atomic_add v4, v233, s[22:23]
	s_mov_b64 exec, s[36:37]
.Lxb_notlast:
	s_and_saveexec_b64 s[28:29], vcc
	s_cbranch_execz .LBB0_739
	v_readlane_b32 s12, v255, 10
	v_readlane_b32 s13, v255, 11
	s_mov_b64 s[36:37], 0
	s_nop 3
	global_load_dword v2, v1, s[12:13] sc1
	s_waitcnt vmcnt(0)
	v_cmp_eq_u32_e32 vcc, v2, v0
	s_and_saveexec_b64 s[30:31], vcc
	s_cbranch_execz .LBB0_738
	s_mov_b32 s2, 1
	s_branch .LBB0_731

.LBB0_741:
	s_or_b64 exec, exec, s[28:29]
	v_readlane_b32 s12, v255, 6
	v_readlane_b32 s13, v255, 7
	s_waitcnt vmcnt(0)
.LBB0_742:
	s_or_b64 exec, exec, s[26:27]
	s_waitcnt lgkmcnt(0)
	s_barrier
	s_mov_b64 s[26:27], -1
	s_and_b64 vcc, exec, s[24:25]
	s_cbranch_vccz .LBB0_704
